# attention tile body: the prefetched next K/V tile is written to its LDS buffer in mid-body (after the QK MFMAs) instead of at the end of the iteration
# baseline (speedup 1.0000x reference)
; #define LAS __attribute__((address_space(3)))
; __device__ __forceinline__ int crow(int r, int hi) { return (r & 3) + 8 * (r >> 2) + 4 * hi; }
; __device__ __forceinline__ void attn_block_unit(LAS unsigned char* lds, const bf16* QB, bf16* OB, const bf16* KB, const bf16* VB, int sb, int hp, int cp, const float* tab, int tid) {
;     ...
;             LAS const unsigned char* kb = lds + (j & 1) * AB_BUF + hsel * AB_HB; LAS const unsigned char* vb = kb + 9216;
;             f32x16 s0, s1;
; #pragma unroll
;             for (int r = 0; r < 16; ++r) { s0[r] = 0.f; s1[r] = 0.f; }
; #pragma unroll
;             for (int d0 = 0; d0 < 4; ++d0) {
;                 const bf16x8 k0 = *(const LAS bf16x8*)(kb + r32 * ATT_VP + (16 * d0 + 8 * hi) * 2), k1 = *(const LAS bf16x8*)(kb + (32 + r32) * ATT_VP + (16 * d0 + 8 * hi) * 2);
;                 s0 = __builtin_amdgcn_mfma_f32_32x32x16_bf16(k0, qfr[d0], s0, 0, 0, 0); s1 = __builtin_amdgcn_mfma_f32_32x32x16_bf16(k1, qfr[d0], s1, 0, 0, 0); }
;             if (t < 6) {
; #pragma unroll
;                 for (int r = 0; r < 16; ++r) { s0[r] += cb; s1[r] += cb; }
;             } else {
;                 const int relb = 64 * (8 - t) + 32 * qh + r32 + 128;
; #pragma unroll
;                 for (int r = 0; r < 16; ++r) { const int i0 = relb - crow(r, hi); s0[r] += btab[i0 > 256 ? 256 : i0]; const int i1 = i0 - 32; s1[r] += btab[i1 > 256 ? 256 : i1]; }
;             }
.LBB0_550:
	s_bitcmp1_b32 s6, 0
	s_cselect_b32 s26, 0x9000, 0
	s_add_i32 s30, s28, s26
	v_add3_u32 v2, s30, v167, v138
	ds_read_b128 v[36:39], v2
	ds_read_b128 v[52:55], v2 offset:4608
	ds_read_b128 v[40:43], v2 offset:32
	ds_read_b128 v[56:59], v2 offset:4640
	ds_read_b128 v[44:47], v2 offset:64
	ds_read_b128 v[60:63], v2 offset:4672
	ds_read_b128 v[48:51], v2 offset:96
	ds_read_b128 v[64:67], v2 offset:4704
	v_add3_u32 v2, s30, v161, v163
	s_waitcnt lgkmcnt(6)
	v_mfma_f32_32x32x16_bf16 v[84:99], v[36:39], v[104:107], 0
	v_mfma_f32_32x32x16_bf16 v[68:83], v[52:55], v[104:107], 0
	s_waitcnt lgkmcnt(4)
	v_mfma_f32_32x32x16_bf16 v[84:99], v[40:43], v[108:111], v[84:99]
	v_mfma_f32_32x32x16_bf16 v[68:83], v[56:59], v[108:111], v[68:83]
	s_waitcnt lgkmcnt(2)
	v_mfma_f32_32x32x16_bf16 v[84:99], v[44:47], v[120:123], v[84:99]
	v_mfma_f32_32x32x16_bf16 v[68:83], v[60:63], v[120:123], v[68:83]
	s_waitcnt lgkmcnt(0)
	v_mfma_f32_32x32x16_bf16 v[84:99], v[48:51], v[124:127], v[84:99]
	v_mfma_f32_32x32x16_bf16 v[68:83], v[64:67], v[124:127], v[68:83]
	ds_read_b64_tr_b16 v[218:219], v2 offset:9216
	ds_read_b64_tr_b16 v[220:221], v2 offset:10368
	ds_read_b64_tr_b16 v[222:223], v2 offset:11520
	ds_read_b64_tr_b16 v[224:225], v2 offset:12672
	ds_read_b64_tr_b16 v[226:227], v2 offset:13824
	ds_read_b64_tr_b16 v[228:229], v2 offset:14976
	ds_read_b64_tr_b16 v[230:231], v2 offset:16128
	ds_read_b64_tr_b16 v[232:233], v2 offset:17280
	ds_read_b64_tr_b16 v[234:235], v2 offset:9280
	ds_read_b64_tr_b16 v[236:237], v2 offset:10432
	ds_read_b64_tr_b16 v[238:239], v2 offset:11584
	ds_read_b64_tr_b16 v[240:241], v2 offset:12736
	ds_read_b64_tr_b16 v[242:243], v2 offset:13888
	ds_read_b64_tr_b16 v[244:245], v2 offset:15040
	ds_read_b64_tr_b16 v[246:247], v2 offset:16192
	ds_read_b64_tr_b16 v[248:249], v2 offset:17344
	s_andn2_b64 vcc, exec, s[14:15]
	s_cbranch_vccnz .Latt_nostage
	s_sub_i32 s26, 0x9000, s26
	v_add_u32_e32 v2, s26, v165
	s_waitcnt vmcnt(3)
	ds_write_b128 v2, v[100:103]
	s_waitcnt vmcnt(1)
	ds_write_b128 v2, v[112:115] offset:9216
	ds_write_b128 v2, v[116:119] offset:18432
	s_waitcnt vmcnt(0)
	ds_write_b128 v2, v[128:131] offset:27648
.Latt_nostage:
	s_cmp_gt_u32 s31, 5
	s_cbranch_scc0 .Latt_t_lt6
	s_cmp_eq_u32 s31, 6
	s_cbranch_scc1 .Latt_t_eq6
	v_add_u32_e32 v2, v135, v213
	s_add_i32 s26, s2, 0x914
	v_add_u32_e32 v67, v135, v189
	v_lshl_add_u32 v2, v2, 2, s26
	v_lshl_add_u32 v67, v67, 2, s26
	ds_read_b32 v36, v2 offset:236
	ds_read_b32 v37, v2 offset:232
	ds_read_b32 v38, v67 offset:228
	ds_read_b32 v39, v67 offset:224
	ds_read_b32 v40, v67 offset:204
	ds_read_b32 v41, v67 offset:200
	ds_read_b32 v42, v67 offset:196
	ds_read_b32 v43, v67 offset:192
	ds_read_b32 v44, v67 offset:172
	ds_read_b32 v45, v67 offset:168
	ds_read_b32 v46, v67 offset:164
	ds_read_b32 v47, v67 offset:160
	ds_read_b32 v48, v67 offset:140
	ds_read_b32 v49, v67 offset:136
	ds_read_b32 v50, v67 offset:132
	ds_read_b32 v51, v67 offset:128
	ds_read_b32 v52, v2 offset:108
	ds_read_b32 v53, v2 offset:104
	ds_read_b32 v54, v67 offset:100
	ds_read_b32 v55, v67 offset:96
	ds_read_b32 v56, v67 offset:76
	ds_read_b32 v57, v67 offset:72
	ds_read_b32 v58, v67 offset:68
	ds_read_b32 v59, v67 offset:64
	ds_read_b32 v60, v67 offset:44
	ds_read_b32 v61, v67 offset:40
	ds_read_b32 v62, v67 offset:36
	ds_read_b32 v63, v67 offset:32
	ds_read_b32 v64, v67 offset:12
	ds_read_b32 v65, v67 offset:8
	ds_read_b32 v66, v67 offset:4
	ds_read_b32 v67, v67 offset:0
	s_waitcnt lgkmcnt(0)
	v_pk_add_f32 v[84:85], v[84:85], v[36:37]
	v_pk_add_f32 v[86:87], v[86:87], v[38:39]
	v_pk_add_f32 v[88:89], v[88:89], v[40:41]
	v_pk_add_f32 v[90:91], v[90:91], v[42:43]
	v_pk_add_f32 v[92:93], v[92:93], v[44:45]
	v_pk_add_f32 v[94:95], v[94:95], v[46:47]
	v_pk_add_f32 v[96:97], v[96:97], v[48:49]
	v_pk_add_f32 v[98:99], v[98:99], v[50:51]
	v_pk_add_f32 v[68:69], v[68:69], v[52:53]
	v_pk_add_f32 v[70:71], v[70:71], v[54:55]
	v_pk_add_f32 v[72:73], v[72:73], v[56:57]
	v_pk_add_f32 v[74:75], v[74:75], v[58:59]
	v_pk_add_f32 v[76:77], v[76:77], v[60:61]
	v_pk_add_f32 v[78:79], v[78:79], v[62:63]
	v_pk_add_f32 v[80:81], v[80:81], v[64:65]
	v_pk_add_f32 v[82:83], v[82:83], v[66:67]
	v_mov_b32_e32 v66, 0
	s_branch .Latt_softmax

; #define LAS __attribute__((address_space(3)))
; __device__ __forceinline__ bf16x8 cat8(s16x4 a, s16x4 b) { return (bf16x8){a[0], a[1], a[2], a[3], b[0], b[1], b[2], b[3]}; }
; __device__ __forceinline__ bf16x8 pack8(const f32x16& v, int o) { u32x4 w; w.x = pk2(v[o], v[o + 1]); w.y = pk2(v[o + 2], v[o + 3]); w.z = pk2(v[o + 4], v[o + 5]); w.w = pk2(v[o + 6], v[o + 7]); return __builtin_bit_cast(bf16x8, w); }
; #define AB_STORE(jj) do { LAS unsigned char* b_ = lds + ((jj) & 1) * AB_BUF + lrow * ATT_VP + lch * 16; *(LAS u32x4*)b_ = kreg0; *(LAS u32x4*)(b_ + 9216) = vreg0; *(LAS u32x4*)(b_ + AB_HB) = kreg1; *(LAS u32x4*)(b_ + AB_HB + 9216) = vreg1; } while (0)
; __device__ __forceinline__ void attn_block_unit(LAS unsigned char* lds, const bf16* QB, bf16* OB, const bf16* KB, const bf16* VB, int sb, int hp, int cp, const float* tab, int tid) {
;     ...
;             const float mn = fmaxf(mrun, tm), sc = __expf(mrun - mn); mrun = mn;
;             float ps = 0.f;
; #pragma unroll
;             for (int r = 0; r < 16; ++r) { s0[r] = __expf(s0[r] - mn); s1[r] = __expf(s1[r] - mn); ps += s0[r] + s1[r]; }
;             lrun = lrun * sc + ps;
; #pragma unroll
;             for (int r = 0; r < 16; ++r) { oT[0][r] *= sc; oT[1][r] *= sc; }
;             bf16x8 pf[4]; pf[0] = pack8(s0, 0); pf[1] = pack8(s0, 8); pf[2] = pack8(s1, 0); pf[3] = pack8(s1, 8);
; #pragma unroll
;             for (int dh = 0; dh < 2; ++dh)
; #pragma unroll
;                 for (int kc = 0; kc < 4; ++kc) {
;                     LAS const unsigned char* p = vb + traddr + (16 * kc) * ATT_VP + dh * 64;
;                     const bf16x8 vf = cat8(tr16(p), tr16(p + 8 * ATT_VP));
;                     oT[dh] = __builtin_amdgcn_mfma_f32_32x32x16_bf16(vf, pf[kc], oT[dh], 0, 0, 0);
;                 }
;         }
;         if (j + 1 < 10) AB_STORE(j + 1);
.Latt_keep_max:
	v_sub_f32_e32 v62, v66, v215
	v_mul_f32_e32 v62, 0x3fb8aa3b, v62
	v_fmamk_f32 v84, v84, 0x3fb8aa3b, v62
	v_fmamk_f32 v85, v85, 0x3fb8aa3b, v62
	v_fmamk_f32 v86, v86, 0x3fb8aa3b, v62
	v_fmamk_f32 v87, v87, 0x3fb8aa3b, v62
	v_fmamk_f32 v88, v88, 0x3fb8aa3b, v62
	v_fmamk_f32 v89, v89, 0x3fb8aa3b, v62
	v_fmamk_f32 v90, v90, 0x3fb8aa3b, v62
	v_fmamk_f32 v91, v91, 0x3fb8aa3b, v62
	v_fmamk_f32 v92, v92, 0x3fb8aa3b, v62
	v_fmamk_f32 v93, v93, 0x3fb8aa3b, v62
	v_fmamk_f32 v94, v94, 0x3fb8aa3b, v62
	v_fmamk_f32 v95, v95, 0x3fb8aa3b, v62
	v_fmamk_f32 v96, v96, 0x3fb8aa3b, v62
	v_fmamk_f32 v97, v97, 0x3fb8aa3b, v62
	v_fmamk_f32 v98, v98, 0x3fb8aa3b, v62
	v_fmamk_f32 v99, v99, 0x3fb8aa3b, v62
	v_fmamk_f32 v68, v68, 0x3fb8aa3b, v62
	v_fmamk_f32 v69, v69, 0x3fb8aa3b, v62
	v_fmamk_f32 v70, v70, 0x3fb8aa3b, v62
	v_fmamk_f32 v71, v71, 0x3fb8aa3b, v62
	v_fmamk_f32 v72, v72, 0x3fb8aa3b, v62
	v_fmamk_f32 v73, v73, 0x3fb8aa3b, v62
	v_fmamk_f32 v74, v74, 0x3fb8aa3b, v62
	v_fmamk_f32 v75, v75, 0x3fb8aa3b, v62
	v_fmamk_f32 v76, v76, 0x3fb8aa3b, v62
	v_fmamk_f32 v77, v77, 0x3fb8aa3b, v62
	v_fmamk_f32 v78, v78, 0x3fb8aa3b, v62
	v_fmamk_f32 v79, v79, 0x3fb8aa3b, v62
	v_fmamk_f32 v80, v80, 0x3fb8aa3b, v62
	v_fmamk_f32 v81, v81, 0x3fb8aa3b, v62
	v_fmamk_f32 v82, v82, 0x3fb8aa3b, v62
	v_fmamk_f32 v83, v83, 0x3fb8aa3b, v62
	v_exp_f32_e32 v84, v84
	v_exp_f32_e32 v85, v85
	v_exp_f32_e32 v86, v86
	v_exp_f32_e32 v87, v87
	v_exp_f32_e32 v88, v88
	v_exp_f32_e32 v89, v89
	v_exp_f32_e32 v90, v90
	v_exp_f32_e32 v91, v91
	v_exp_f32_e32 v92, v92
	v_exp_f32_e32 v93, v93
	v_exp_f32_e32 v94, v94
	v_exp_f32_e32 v95, v95
	v_exp_f32_e32 v96, v96
	v_exp_f32_e32 v97, v97
	v_exp_f32_e32 v98, v98
	v_exp_f32_e32 v99, v99
	v_exp_f32_e32 v68, v68
	v_exp_f32_e32 v69, v69
	v_exp_f32_e32 v70, v70
	v_exp_f32_e32 v71, v71
	v_exp_f32_e32 v72, v72
	v_exp_f32_e32 v73, v73
	v_exp_f32_e32 v74, v74
	v_exp_f32_e32 v75, v75
	v_exp_f32_e32 v76, v76
	v_exp_f32_e32 v77, v77
	v_exp_f32_e32 v78, v78
	v_exp_f32_e32 v79, v79
	v_exp_f32_e32 v80, v80
	v_exp_f32_e32 v81, v81
	v_exp_f32_e32 v82, v82
	v_exp_f32_e32 v83, v83
	v_pk_add_f32 v[36:37], v[84:85], v[86:87]
	v_pk_add_f32 v[38:39], v[88:89], v[90:91]
	v_pk_add_f32 v[40:41], v[92:93], v[94:95]
	v_pk_add_f32 v[42:43], v[96:97], v[98:99]
	v_pk_add_f32 v[44:45], v[68:69], v[70:71]
	v_pk_add_f32 v[46:47], v[72:73], v[74:75]
	v_pk_add_f32 v[48:49], v[76:77], v[78:79]
	v_pk_add_f32 v[50:51], v[80:81], v[82:83]
	v_pk_add_f32 v[54:55], v[36:37], v[38:39]
	v_pk_add_f32 v[56:57], v[40:41], v[42:43]
	v_pk_add_f32 v[58:59], v[44:45], v[46:47]
	v_pk_add_f32 v[60:61], v[48:49], v[50:51]
	v_pk_add_f32 v[54:55], v[54:55], v[56:57]
	v_pk_add_f32 v[58:59], v[58:59], v[60:61]
	v_pk_add_f32 v[54:55], v[54:55], v[58:59]
	v_add_f32_e32 v54, v54, v55
	v_add_f32_e32 v214, v214, v54
	v_cvt_pk_bf16_f32 v36, v84, v85
	v_cvt_pk_bf16_f32 v37, v86, v87
	v_cvt_pk_bf16_f32 v38, v88, v89
	v_cvt_pk_bf16_f32 v39, v90, v91
	v_cvt_pk_bf16_f32 v40, v92, v93
	v_cvt_pk_bf16_f32 v41, v94, v95
	v_cvt_pk_bf16_f32 v42, v96, v97
	v_cvt_pk_bf16_f32 v43, v98, v99
	v_cvt_pk_bf16_f32 v44, v68, v69
	v_cvt_pk_bf16_f32 v45, v70, v71
	v_cvt_pk_bf16_f32 v46, v72, v73
	v_cvt_pk_bf16_f32 v47, v74, v75
	v_cvt_pk_bf16_f32 v48, v76, v77
	v_cvt_pk_bf16_f32 v49, v78, v79
	v_cvt_pk_bf16_f32 v50, v80, v81
	v_cvt_pk_bf16_f32 v51, v82, v83
	s_waitcnt lgkmcnt(0)
	v_mfma_f32_32x32x16_bf16 v[20:35], v[218:221], v[36:39], v[20:35]
	v_mfma_f32_32x32x16_bf16 v[4:19], v[234:237], v[36:39], v[4:19]
	v_mfma_f32_32x32x16_bf16 v[20:35], v[222:225], v[40:43], v[20:35]
	v_mfma_f32_32x32x16_bf16 v[4:19], v[238:241], v[40:43], v[4:19]
	v_mfma_f32_32x32x16_bf16 v[20:35], v[226:229], v[44:47], v[20:35]
	v_mfma_f32_32x32x16_bf16 v[4:19], v[242:245], v[44:47], v[4:19]
	v_mfma_f32_32x32x16_bf16 v[20:35], v[230:233], v[48:51], v[20:35]
	v_mfma_f32_32x32x16_bf16 v[4:19], v[246:249], v[48:51], v[4:19]
	s_add_i32 s14, s6, 1
	s_branch .LBB0_547

; template <class Epi, class Sched, bool ALIGN_EPI = false, bool SP2 = false>
; __device__ __forceinline__ void gemm_phase(PG8_LAS unsigned char* lds, const Gemm g, const Sched& S, const Epi& E, const int tid_arg) {
;     ...
; #pragma unroll
;         for (int a = 0; a < 2; ++a)
; #pragma unroll
;             for (int b = 0; b < 2; ++b)
; #pragma unroll
;                 for (int m = 0; m < 4; ++m)
; #pragma unroll
;                     for (int n = 0; n < 2; ++n) acc[a][b][m][n] = (f32x4){0.f, 0.f, 0.f, 0.f};
.LBB0_763:
	s_ashr_i32 s27, s26, 31
	s_lshl_b64 s[28:29], s[26:27], 19
	s_add_u32 s28, s3, s28
	s_addc_u32 s29, s6, s29
	s_and_b64 s[30:31], s[10:11], exec
	s_cselect_b32 s27, s29, s5
	s_cselect_b32 s48, s28, s4
	s_ashr_i32 s25, s24, 31
	s_lshl_b64 s[30:31], s[24:25], 19
	s_add_u32 s30, s7, s30
	s_addc_u32 s31, s38, s31
	s_and_b64 s[36:37], s[10:11], exec
	s_cselect_b32 s25, s31, s35
	s_cselect_b32 s49, s30, s34
	s_add_u32 s4, s4, 0x40080
	s_addc_u32 s5, s5, 0
	s_add_u32 s50, s34, 0x100
	v_mov_b32_e32 v4, 0
	s_addc_u32 s51, s35, 0
	s_mov_b32 s52, -2
	v_mov_b32_e32 v5, v4
	v_mov_b32_e32 v6, v4
	v_mov_b32_e32 v7, v4
	v_mov_b32_e32 v8, v4
	v_mov_b32_e32 v9, v4
	v_mov_b32_e32 v10, v4
	v_mov_b32_e32 v11, v4
	v_mov_b32_e32 v20, v4
	v_mov_b32_e32 v21, v4
	v_mov_b32_e32 v22, v4
	v_mov_b32_e32 v23, v4
	v_mov_b32_e32 v24, v4
	v_mov_b32_e32 v25, v4
	v_mov_b32_e32 v26, v4
	v_mov_b32_e32 v27, v4
	v_mov_b32_e32 v36, v4
	v_mov_b32_e32 v37, v4
	v_mov_b32_e32 v38, v4
	v_mov_b32_e32 v39, v4
	v_mov_b32_e32 v40, v4
	v_mov_b32_e32 v41, v4
	v_mov_b32_e32 v42, v4
	v_mov_b32_e32 v43, v4
	v_mov_b32_e32 v52, v4
	v_mov_b32_e32 v53, v4
	v_mov_b32_e32 v54, v4
	v_mov_b32_e32 v55, v4
	v_mov_b32_e32 v56, v4
	v_mov_b32_e32 v57, v4
	v_mov_b32_e32 v58, v4
	v_mov_b32_e32 v59, v4
	v_mov_b32_e32 v12, v4
	v_mov_b32_e32 v13, v4
	v_mov_b32_e32 v14, v4
	v_mov_b32_e32 v15, v4
	v_mov_b32_e32 v16, v4
	v_mov_b32_e32 v17, v4
	v_mov_b32_e32 v18, v4
	v_mov_b32_e32 v19, v4
	v_mov_b32_e32 v28, v4
	v_mov_b32_e32 v29, v4
	v_mov_b32_e32 v30, v4
	v_mov_b32_e32 v31, v4
	v_mov_b32_e32 v32, v4
	v_mov_b32_e32 v33, v4
	v_mov_b32_e32 v34, v4
	v_mov_b32_e32 v35, v4
	v_mov_b32_e32 v44, v4
	v_mov_b32_e32 v45, v4
	v_mov_b32_e32 v46, v4
	v_mov_b32_e32 v47, v4
	v_mov_b32_e32 v48, v4
	v_mov_b32_e32 v49, v4
	v_mov_b32_e32 v50, v4
	v_mov_b32_e32 v51, v4
	v_mov_b32_e32 v60, v4
	v_mov_b32_e32 v61, v4
	v_mov_b32_e32 v62, v4
	v_mov_b32_e32 v63, v4
	v_mov_b32_e32 v64, v4
	v_mov_b32_e32 v65, v4
	v_mov_b32_e32 v66, v4
	v_mov_b32_e32 v67, v4
	v_mov_b32_e32 v68, v4
	v_mov_b32_e32 v69, v4
	v_mov_b32_e32 v70, v4
	v_mov_b32_e32 v71, v4
	v_mov_b32_e32 v72, v4
	v_mov_b32_e32 v73, v4
	v_mov_b32_e32 v74, v4
	v_mov_b32_e32 v75, v4
	v_mov_b32_e32 v84, v4
	v_mov_b32_e32 v85, v4
	v_mov_b32_e32 v86, v4
	v_mov_b32_e32 v87, v4
	v_mov_b32_e32 v88, v4
	v_mov_b32_e32 v89, v4
	v_mov_b32_e32 v90, v4
	v_mov_b32_e32 v91, v4
	v_mov_b32_e32 v100, v4
	v_mov_b32_e32 v101, v4
	v_mov_b32_e32 v102, v4
	v_mov_b32_e32 v103, v4
	v_mov_b32_e32 v104, v4
	v_mov_b32_e32 v105, v4
	v_mov_b32_e32 v106, v4
	v_mov_b32_e32 v107, v4
	v_mov_b32_e32 v116, v4
	v_mov_b32_e32 v117, v4
	v_mov_b32_e32 v118, v4
	v_mov_b32_e32 v119, v4
	s_waitcnt vmcnt(0)
	v_mov_b32_e32 v120, v4
	v_mov_b32_e32 v121, v4
	v_mov_b32_e32 v122, v4
	v_mov_b32_e32 v123, v4
	v_mov_b32_e32 v76, v4
	v_mov_b32_e32 v77, v4
	v_mov_b32_e32 v78, v4
	v_mov_b32_e32 v79, v4
	v_mov_b32_e32 v80, v4
	v_mov_b32_e32 v81, v4
	v_mov_b32_e32 v82, v4
	v_mov_b32_e32 v83, v4
	v_mov_b32_e32 v92, v4
	v_mov_b32_e32 v93, v4
	v_mov_b32_e32 v94, v4
	v_mov_b32_e32 v95, v4
	v_mov_b32_e32 v96, v4
	v_mov_b32_e32 v97, v4
	v_mov_b32_e32 v98, v4
	v_mov_b32_e32 v99, v4
	v_mov_b32_e32 v108, v4
	v_mov_b32_e32 v109, v4
	v_mov_b32_e32 v110, v4
	v_mov_b32_e32 v111, v4
	v_mov_b32_e32 v112, v4
	v_mov_b32_e32 v113, v4
	v_mov_b32_e32 v114, v4
	v_mov_b32_e32 v115, v4
	v_mov_b32_e32 v124, v4
	v_mov_b32_e32 v125, v4
	v_mov_b32_e32 v126, v4
	v_mov_b32_e32 v127, v4
	v_mov_b32_e32 v128, v4
	v_mov_b32_e32 v129, v4
	v_mov_b32_e32 v130, v4
	v_mov_b32_e32 v131, v4
	s_nop 0
	s_nop 0
	s_nop 0
	s_nop 0
	s_nop 0
	s_nop 0
	s_nop 0
	s_nop 0
	s_nop 0
	s_nop 0
